# SSD: next-chunk load addresses advanced incrementally (5 persistent address pairs) instead of recomputed each step, on top of v46
# baseline (speedup 1.0000x reference)
.LBB0_1040:
	s_xor_b64 s[24:25], s[22:23], -1
	s_xor_b64 s[22:23], s[78:79], -1
	s_add_i32 s47, s47, 1
	s_cmp_eq_u32 s35, 0
	s_cselect_b64 s[78:79], -1, 0
	s_andn2_b64 vcc, exec, s[24:25]
	s_mov_b64 s[24:25], -1
	s_cbranch_vccnz .LBB0_1113
	s_and_b64 s[24:25], s[78:79], exec
	s_mov_b32 s24, 0x1e400
	s_cselect_b32 s24, 0x1a000, s24
	v_add_u32_e32 v94, s24, v149
	s_waitcnt vmcnt(2)
	ds_read_b128 v[66:69], v94
	ds_read_b128 v[98:101], v161
	ds_read_b128 v[70:73], v94 offset:4352
	ds_read_b128 v[74:77], v94 offset:8704
	ds_read_b128 v[82:85], v94 offset:64
	ds_read_b128 v[102:105], v161 offset:64
	s_waitcnt lgkmcnt(4)
	v_mfma_f32_16x16x32_bf16 v[66:69], v[66:69], v[98:101], 0
	ds_read_b128 v[78:81], v94 offset:13056
	s_andn2_b64 vcc, exec, s[62:63]
	s_waitcnt lgkmcnt(4)
	v_mfma_f32_16x16x32_bf16 v[70:73], v[70:73], v[98:101], 0
	s_waitcnt lgkmcnt(1)
	v_mfma_f32_16x16x32_bf16 v[66:69], v[82:85], v[102:105], v[66:69]
	ds_read_b128 v[82:85], v94 offset:4416
	v_mfma_f32_16x16x32_bf16 v[74:77], v[74:77], v[98:101], 0
	s_waitcnt lgkmcnt(0)
	v_mfma_f32_16x16x32_bf16 v[70:73], v[82:85], v[102:105], v[70:73]
	ds_read_b128 v[82:85], v94 offset:8768
	v_mfma_f32_16x16x32_bf16 v[78:81], v[78:81], v[98:101], 0
	s_waitcnt lgkmcnt(0)
	v_mfma_f32_16x16x32_bf16 v[74:77], v[82:85], v[102:105], v[74:77]
	ds_read_b128 v[82:85], v94 offset:13120
	ds_read_b128 v[86:89], v94 offset:128
	s_waitcnt lgkmcnt(1)
	v_mfma_f32_16x16x32_bf16 v[78:81], v[82:85], v[102:105], v[78:81]
	ds_read_b128 v[106:109], v161 offset:128
	ds_read_b128 v[82:85], v94 offset:4480
	s_waitcnt lgkmcnt(1)
	v_mfma_f32_16x16x32_bf16 v[66:69], v[86:89], v[106:109], v[66:69]
	ds_read_b128 v[86:89], v94 offset:8832
	s_waitcnt lgkmcnt(1)
	v_mfma_f32_16x16x32_bf16 v[70:73], v[82:85], v[106:109], v[70:73]
	ds_read_b128 v[82:85], v94 offset:13184
	s_waitcnt lgkmcnt(1)
	v_mfma_f32_16x16x32_bf16 v[74:77], v[86:89], v[106:109], v[74:77]
	ds_read_b128 v[86:89], v94 offset:192
	ds_read_b128 v[90:93], v94 offset:4544
	ds_read_b128 v[110:113], v161 offset:192
	s_waitcnt lgkmcnt(3)
	v_mfma_f32_16x16x32_bf16 v[82:85], v[82:85], v[106:109], v[78:81]
	s_waitcnt lgkmcnt(0)
	v_mfma_f32_16x16x32_bf16 v[66:69], v[86:89], v[110:113], v[66:69]
	s_nop 0
	ds_read_b128 v[78:81], v94 offset:8896
	ds_read_b128 v[86:89], v94 offset:13248
	v_mfma_f32_16x16x32_bf16 v[70:73], v[90:93], v[110:113], v[70:73]
	s_waitcnt lgkmcnt(1)
	v_mfma_f32_16x16x32_bf16 v[78:81], v[78:81], v[110:113], v[74:77]
	s_waitcnt lgkmcnt(0)
	v_mfma_f32_16x16x32_bf16 v[74:77], v[86:89], v[110:113], v[82:85]
	s_cbranch_vccnz .LBB0_1043
	s_cmp_gt_u32 s47, 2
	s_cbranch_scc1 .Lmy_sdfast_a
	s_and_b64 s[24:25], s[92:93], exec
	s_cselect_b32 s24, 1, 35
	s_sub_i32 s24, s24, s47
	s_lshl_b32 s25, s24, 7
	s_or_b32 s26, s25, s0
	s_add_i32 s25, s25, s1
	s_cmp_lt_u32 s24, 2
	s_cselect_b32 s24, s26, s25
	v_add_u32_e32 v0, s24, v137
	v_ashrrev_i32_e32 v1, 31, v0
	v_lshlrev_b64 v[0:1], 13, v[0:1]
	v_add_u32_e32 v8, s24, v138
	v_lshl_add_u64 v[0:1], s[44:45], 0, v[0:1]
	s_mov_b32 s83, s67
	v_ashrrev_i32_e32 v9, 31, v8
	v_lshl_add_u64 v[0:1], v[0:1], 0, s[82:83]
	v_lshlrev_b64 v[8:9], 13, v[8:9]
	v_add_u32_e32 v16, s24, v139
	v_lshl_add_u64 v[0:1], v[0:1], 0, v[64:65]
	s_movk_i32 s25, 0x1000
	v_lshl_add_u64 v[8:9], s[44:45], 0, v[8:9]
	v_ashrrev_i32_e32 v17, 31, v16
	v_add_co_u32_e32 v4, vcc, s25, v0
	v_lshl_add_u64 v[8:9], v[8:9], 0, s[82:83]
	v_lshlrev_b64 v[16:17], 13, v[16:17]
	v_add_u32_e32 v24, s24, v140
	v_addc_co_u32_e32 v5, vcc, 0, v1, vcc
	v_lshl_add_u64 v[8:9], v[8:9], 0, v[64:65]
	v_lshl_add_u64 v[16:17], s[44:45], 0, v[16:17]
	v_ashrrev_i32_e32 v25, 31, v24
	v_add_co_u32_e32 v12, vcc, s25, v8
	v_lshl_add_u64 v[16:17], v[16:17], 0, s[82:83]
	v_lshlrev_b64 v[24:25], 13, v[24:25]
	v_addc_co_u32_e32 v13, vcc, 0, v9, vcc
	v_lshl_add_u64 v[16:17], v[16:17], 0, v[64:65]
	v_lshl_add_u64 v[24:25], s[44:45], 0, v[24:25]
	v_add_co_u32_e32 v20, vcc, s25, v16
	v_lshl_add_u64 v[24:25], v[24:25], 0, s[82:83]
	v_add_u32_e32 v32, s24, v136
	v_addc_co_u32_e32 v21, vcc, 0, v17, vcc
	v_lshl_add_u64 v[24:25], v[24:25], 0, v[64:65]
	v_ashrrev_i32_e32 v33, 31, v32
	v_add_co_u32_e32 v28, vcc, s25, v24
	v_lshlrev_b64 v[32:33], 13, v[32:33]
	s_nop 0
	v_addc_co_u32_e32 v29, vcc, 0, v25, vcc
	v_lshl_add_u64 v[36:37], v[130:131], 0, v[32:33]
	v_mov_b64_e32 v[222:223], v[4:5]
	v_mov_b64_e32 v[224:225], v[12:13]
	v_mov_b64_e32 v[226:227], v[20:21]
	v_mov_b64_e32 v[228:229], v[28:29]
	v_mov_b64_e32 v[230:231], v[36:37]
	s_branch .Lmy_sdload_a
.Lmy_sdfast_a:
	s_mov_b32 s83, s67
	s_mov_b32 s100, 0xfff00000
	s_mov_b32 s101, -1
	v_lshl_add_u64 v[222:223], v[222:223], 0, s[100:101]
	v_lshl_add_u64 v[224:225], v[224:225], 0, s[100:101]
	v_lshl_add_u64 v[226:227], v[226:227], 0, s[100:101]
	v_lshl_add_u64 v[228:229], v[228:229], 0, s[100:101]
	v_lshl_add_u64 v[230:231], v[230:231], 0, s[100:101]
.Lmy_sdload_a:
	global_load_dwordx4 v[0:3], v[222:223], off offset:2048
	global_load_dwordx4 v[4:7], v[222:223], off
	global_load_dwordx4 v[8:11], v[224:225], off offset:2048
	global_load_dwordx4 v[12:15], v[224:225], off
	global_load_dwordx4 v[16:19], v[226:227], off offset:2048
	global_load_dwordx4 v[20:23], v[226:227], off
	global_load_dwordx4 v[24:27], v[228:229], off offset:2048
	global_load_dwordx4 v[28:31], v[228:229], off
	global_load_dwordx4 v[32:35], v[230:231], off offset:16
	global_load_dwordx4 v[36:39], v[230:231], off
	s_mov_b32 s83, 0x41a00000

.LBB0_1113:
	s_and_b64 vcc, exec, s[24:25]
	s_cbranch_vccz .LBB0_1009
	s_and_b64 s[22:23], s[92:93], exec
	s_cselect_b32 s22, 1, 35
	s_sub_i32 s22, s22, s47
	s_lshl_b32 s23, s22, 7
	s_or_b32 s24, s23, s0
	s_add_i32 s23, s23, s1
	s_cmp_lt_u32 s22, 2
	s_cselect_b32 s22, s24, s23
	v_add_u32_e32 v0, s22, v137
	v_ashrrev_i32_e32 v1, 31, v0
	v_lshlrev_b64 v[0:1], 13, v[0:1]
	v_add_u32_e32 v8, s22, v138
	v_lshl_add_u64 v[0:1], s[44:45], 0, v[0:1]
	s_mov_b32 s83, s67
	v_ashrrev_i32_e32 v9, 31, v8
	v_lshl_add_u64 v[0:1], v[0:1], 0, s[82:83]
	v_lshlrev_b64 v[8:9], 13, v[8:9]
	v_add_u32_e32 v16, s22, v139
	v_lshl_add_u64 v[0:1], v[0:1], 0, v[64:65]
	s_movk_i32 s23, 0x1000
	v_lshl_add_u64 v[8:9], s[44:45], 0, v[8:9]
	v_ashrrev_i32_e32 v17, 31, v16
	v_add_co_u32_e32 v4, vcc, s23, v0
	v_lshl_add_u64 v[8:9], v[8:9], 0, s[82:83]
	v_lshlrev_b64 v[16:17], 13, v[16:17]
	v_add_u32_e32 v24, s22, v140
	v_addc_co_u32_e32 v5, vcc, 0, v1, vcc
	v_lshl_add_u64 v[8:9], v[8:9], 0, v[64:65]
	v_lshl_add_u64 v[16:17], s[44:45], 0, v[16:17]
	v_ashrrev_i32_e32 v25, 31, v24
	v_add_co_u32_e32 v12, vcc, s23, v8
	v_lshl_add_u64 v[16:17], v[16:17], 0, s[82:83]
	v_lshlrev_b64 v[24:25], 13, v[24:25]
	v_addc_co_u32_e32 v13, vcc, 0, v9, vcc
	v_lshl_add_u64 v[16:17], v[16:17], 0, v[64:65]
	v_lshl_add_u64 v[24:25], s[44:45], 0, v[24:25]
	v_add_co_u32_e32 v20, vcc, s23, v16
	v_lshl_add_u64 v[24:25], v[24:25], 0, s[82:83]
	v_add_u32_e32 v32, s22, v136
	v_addc_co_u32_e32 v21, vcc, 0, v17, vcc
	v_lshl_add_u64 v[24:25], v[24:25], 0, v[64:65]
	v_ashrrev_i32_e32 v33, 31, v32
	v_add_co_u32_e32 v28, vcc, s23, v24
	v_lshlrev_b64 v[32:33], 13, v[32:33]
	s_nop 0
	v_addc_co_u32_e32 v29, vcc, 0, v25, vcc
	v_lshl_add_u64 v[36:37], v[130:131], 0, v[32:33]
	v_mov_b64_e32 v[222:223], v[4:5]
	v_mov_b64_e32 v[224:225], v[12:13]
	v_mov_b64_e32 v[226:227], v[20:21]
	v_mov_b64_e32 v[228:229], v[28:29]
	v_mov_b64_e32 v[230:231], v[36:37]
	global_load_dwordx4 v[0:3], v[4:5], off offset:2048
	s_nop 0
	global_load_dwordx4 v[4:7], v[4:5], off
	s_nop 0
	global_load_dwordx4 v[8:11], v[12:13], off offset:2048
	s_nop 0
	global_load_dwordx4 v[12:15], v[12:13], off
	s_nop 0
	global_load_dwordx4 v[16:19], v[20:21], off offset:2048
	s_nop 0
	global_load_dwordx4 v[20:23], v[20:21], off
	s_nop 0
	global_load_dwordx4 v[24:27], v[28:29], off offset:2048
	s_nop 0
	global_load_dwordx4 v[28:31], v[28:29], off
	s_nop 0
	global_load_dwordx4 v[32:35], v[36:37], off offset:16
	s_nop 0
	global_load_dwordx4 v[36:39], v[36:37], off
	s_mov_b32 s83, 0x41a00000
	s_mov_b32 s26, s66
	s_branch .LBB0_1009

.LBB0_1162:
	s_xor_b64 s[24:25], s[22:23], -1
	s_xor_b64 s[36:37], s[36:37], -1
	s_add_i32 s26, s34, 1
	s_cmp_eq_u32 s83, 0
	s_cselect_b64 s[22:23], -1, 0
	s_andn2_b64 vcc, exec, s[24:25]
	s_mov_b64 s[24:25], -1
	s_cbranch_vccnz .LBB0_1235
	s_and_b64 s[24:25], s[22:23], exec
	s_mov_b32 s24, 0x1e400
	s_cselect_b32 s24, 0x1a000, s24
	v_add_u32_e32 v94, s24, v151
	s_waitcnt vmcnt(2)
	ds_read_b128 v[66:69], v94
	ds_read_b128 v[102:105], v161
	ds_read_b128 v[70:73], v94 offset:4352
	ds_read_b128 v[74:77], v94 offset:8704
	ds_read_b128 v[82:85], v94 offset:64
	ds_read_b128 v[106:109], v161 offset:64
	s_waitcnt lgkmcnt(4)
	v_mfma_f32_16x16x32_bf16 v[66:69], v[66:69], v[102:105], 0
	ds_read_b128 v[78:81], v94 offset:13056
	s_andn2_b64 vcc, exec, s[20:21]
	s_waitcnt lgkmcnt(4)
	v_mfma_f32_16x16x32_bf16 v[70:73], v[70:73], v[102:105], 0
	s_waitcnt lgkmcnt(1)
	v_mfma_f32_16x16x32_bf16 v[66:69], v[82:85], v[106:109], v[66:69]
	ds_read_b128 v[82:85], v94 offset:4416
	v_mfma_f32_16x16x32_bf16 v[74:77], v[74:77], v[102:105], 0
	s_waitcnt lgkmcnt(0)
	v_mfma_f32_16x16x32_bf16 v[70:73], v[82:85], v[106:109], v[70:73]
	ds_read_b128 v[82:85], v94 offset:8768
	v_mfma_f32_16x16x32_bf16 v[78:81], v[78:81], v[102:105], 0
	s_waitcnt lgkmcnt(0)
	v_mfma_f32_16x16x32_bf16 v[74:77], v[82:85], v[106:109], v[74:77]
	ds_read_b128 v[82:85], v94 offset:13120
	ds_read_b128 v[86:89], v94 offset:128
	s_waitcnt lgkmcnt(1)
	v_mfma_f32_16x16x32_bf16 v[78:81], v[82:85], v[106:109], v[78:81]
	ds_read_b128 v[110:113], v161 offset:128
	ds_read_b128 v[82:85], v94 offset:4480
	s_waitcnt lgkmcnt(1)
	v_mfma_f32_16x16x32_bf16 v[66:69], v[86:89], v[110:113], v[66:69]
	ds_read_b128 v[86:89], v94 offset:8832
	s_waitcnt lgkmcnt(1)
	v_mfma_f32_16x16x32_bf16 v[70:73], v[82:85], v[110:113], v[70:73]
	ds_read_b128 v[82:85], v94 offset:13184
	s_waitcnt lgkmcnt(1)
	v_mfma_f32_16x16x32_bf16 v[86:89], v[86:89], v[110:113], v[74:77]
	s_nop 2
	ds_read_b128 v[74:77], v94 offset:192
	ds_read_b128 v[90:93], v94 offset:4544
	ds_read_b128 v[126:129], v161 offset:192
	s_waitcnt lgkmcnt(3)
	v_mfma_f32_16x16x32_bf16 v[82:85], v[82:85], v[110:113], v[78:81]
	s_waitcnt lgkmcnt(0)
	v_mfma_f32_16x16x32_bf16 v[78:81], v[74:77], v[126:129], v[66:69]
	s_nop 2
	ds_read_b128 v[66:69], v94 offset:8896
	v_mfma_f32_16x16x32_bf16 v[74:77], v[90:93], v[126:129], v[70:73]
	ds_read_b128 v[90:93], v94 offset:13248
	s_waitcnt lgkmcnt(1)
	v_mfma_f32_16x16x32_bf16 v[70:73], v[66:69], v[126:129], v[86:89]
	s_waitcnt lgkmcnt(0)
	v_mfma_f32_16x16x32_bf16 v[66:69], v[90:93], v[126:129], v[82:85]
	s_cbranch_vccnz .LBB0_1165
	s_cmp_gt_u32 s34, 1
	s_cbranch_scc1 .Lmy_sdfast_b
	s_lshl_b32 s24, s26, 7
	s_and_b64 s[20:21], s[56:57], exec
	s_movk_i32 s21, 0xff00
	s_cselect_b32 s20, 8, 12
	s_cselect_b32 s21, 0x4000, s21
	s_lshl_b32 s20, s31, s20
	s_add_i32 s21, s24, s21
	s_add_i32 s21, s21, s20
	v_add_u32_e32 v0, s21, v139
	v_ashrrev_i32_e32 v1, 31, v0
	v_lshlrev_b64 v[0:1], 13, v[0:1]
	v_add_u32_e32 v8, s21, v140
	v_lshl_add_u64 v[0:1], s[44:45], 0, v[0:1]
	s_mov_b32 s83, s67
	v_ashrrev_i32_e32 v9, 31, v8
	v_lshl_add_u64 v[0:1], v[0:1], 0, s[82:83]
	v_lshlrev_b64 v[8:9], 13, v[8:9]
	v_add_u32_e32 v16, s21, v141
	v_lshl_add_u64 v[0:1], v[0:1], 0, v[64:65]
	s_movk_i32 s20, 0x1000
	v_lshl_add_u64 v[8:9], s[44:45], 0, v[8:9]
	v_ashrrev_i32_e32 v17, 31, v16
	v_add_co_u32_e32 v4, vcc, s20, v0
	v_lshl_add_u64 v[8:9], v[8:9], 0, s[82:83]
	v_lshlrev_b64 v[16:17], 13, v[16:17]
	v_add_u32_e32 v24, s21, v142
	v_addc_co_u32_e32 v5, vcc, 0, v1, vcc
	v_lshl_add_u64 v[8:9], v[8:9], 0, v[64:65]
	v_lshl_add_u64 v[16:17], s[44:45], 0, v[16:17]
	v_ashrrev_i32_e32 v25, 31, v24
	v_add_co_u32_e32 v12, vcc, s20, v8
	v_lshl_add_u64 v[16:17], v[16:17], 0, s[82:83]
	v_lshlrev_b64 v[24:25], 13, v[24:25]
	v_addc_co_u32_e32 v13, vcc, 0, v9, vcc
	v_lshl_add_u64 v[16:17], v[16:17], 0, v[64:65]
	v_lshl_add_u64 v[24:25], s[44:45], 0, v[24:25]
	v_add_co_u32_e32 v20, vcc, s20, v16
	v_lshl_add_u64 v[24:25], v[24:25], 0, s[82:83]
	v_add_u32_e32 v32, s21, v138
	v_addc_co_u32_e32 v21, vcc, 0, v17, vcc
	v_lshl_add_u64 v[24:25], v[24:25], 0, v[64:65]
	v_ashrrev_i32_e32 v33, 31, v32
	v_add_co_u32_e32 v28, vcc, s20, v24
	v_lshlrev_b64 v[32:33], 13, v[32:33]
	s_nop 0
	v_addc_co_u32_e32 v29, vcc, 0, v25, vcc
	v_lshl_add_u64 v[36:37], v[132:133], 0, v[32:33]
	v_mov_b64_e32 v[222:223], v[4:5]
	v_mov_b64_e32 v[224:225], v[12:13]
	v_mov_b64_e32 v[226:227], v[20:21]
	v_mov_b64_e32 v[228:229], v[28:29]
	v_mov_b64_e32 v[230:231], v[36:37]
	s_branch .Lmy_sdload_b
.Lmy_sdfast_b:
	s_mov_b32 s83, s67
	s_mov_b32 s100, 0x100000
	s_mov_b32 s101, 0
	v_lshl_add_u64 v[222:223], v[222:223], 0, s[100:101]
	v_lshl_add_u64 v[224:225], v[224:225], 0, s[100:101]
	v_lshl_add_u64 v[226:227], v[226:227], 0, s[100:101]
	v_lshl_add_u64 v[228:229], v[228:229], 0, s[100:101]
	v_lshl_add_u64 v[230:231], v[230:231], 0, s[100:101]
.Lmy_sdload_b:
	global_load_dwordx4 v[0:3], v[222:223], off offset:2048
	global_load_dwordx4 v[4:7], v[222:223], off
	global_load_dwordx4 v[8:11], v[224:225], off offset:2048
	global_load_dwordx4 v[12:15], v[224:225], off
	global_load_dwordx4 v[16:19], v[226:227], off offset:2048
	global_load_dwordx4 v[20:23], v[226:227], off
	global_load_dwordx4 v[24:27], v[228:229], off offset:2048
	global_load_dwordx4 v[28:31], v[228:229], off
	global_load_dwordx4 v[32:35], v[230:231], off offset:16
	global_load_dwordx4 v[36:39], v[230:231], off

.LBB0_1235:
	s_and_b64 vcc, exec, s[24:25]
	s_cbranch_vccz .LBB0_1237
	s_lshl_b32 s24, s26, 7
	s_and_b64 s[20:21], s[56:57], exec
	s_movk_i32 s21, 0xff00
	s_cselect_b32 s20, 8, 12
	s_cselect_b32 s21, 0x4000, s21
	s_lshl_b32 s20, s31, s20
	s_add_i32 s21, s24, s21
	s_add_i32 s21, s21, s20
	v_add_u32_e32 v0, s21, v139
	v_ashrrev_i32_e32 v1, 31, v0
	v_lshlrev_b64 v[0:1], 13, v[0:1]
	v_add_u32_e32 v8, s21, v140
	v_lshl_add_u64 v[0:1], s[44:45], 0, v[0:1]
	s_mov_b32 s83, s67
	v_ashrrev_i32_e32 v9, 31, v8
	v_lshl_add_u64 v[0:1], v[0:1], 0, s[82:83]
	v_lshlrev_b64 v[8:9], 13, v[8:9]
	v_add_u32_e32 v16, s21, v141
	v_lshl_add_u64 v[0:1], v[0:1], 0, v[64:65]
	s_movk_i32 s20, 0x1000
	v_lshl_add_u64 v[8:9], s[44:45], 0, v[8:9]
	v_ashrrev_i32_e32 v17, 31, v16
	v_add_co_u32_e32 v4, vcc, s20, v0
	v_lshl_add_u64 v[8:9], v[8:9], 0, s[82:83]
	v_lshlrev_b64 v[16:17], 13, v[16:17]
	v_add_u32_e32 v24, s21, v142
	v_addc_co_u32_e32 v5, vcc, 0, v1, vcc
	v_lshl_add_u64 v[8:9], v[8:9], 0, v[64:65]
	v_lshl_add_u64 v[16:17], s[44:45], 0, v[16:17]
	v_ashrrev_i32_e32 v25, 31, v24
	v_add_co_u32_e32 v12, vcc, s20, v8
	v_lshl_add_u64 v[16:17], v[16:17], 0, s[82:83]
	v_lshlrev_b64 v[24:25], 13, v[24:25]
	v_addc_co_u32_e32 v13, vcc, 0, v9, vcc
	v_lshl_add_u64 v[16:17], v[16:17], 0, v[64:65]
	v_lshl_add_u64 v[24:25], s[44:45], 0, v[24:25]
	v_add_co_u32_e32 v20, vcc, s20, v16
	v_lshl_add_u64 v[24:25], v[24:25], 0, s[82:83]
	v_add_u32_e32 v32, s21, v138
	v_addc_co_u32_e32 v21, vcc, 0, v17, vcc
	v_lshl_add_u64 v[24:25], v[24:25], 0, v[64:65]
	v_ashrrev_i32_e32 v33, 31, v32
	v_add_co_u32_e32 v28, vcc, s20, v24
	v_lshlrev_b64 v[32:33], 13, v[32:33]
	s_nop 0
	v_addc_co_u32_e32 v29, vcc, 0, v25, vcc
	v_lshl_add_u64 v[36:37], v[132:133], 0, v[32:33]
	v_mov_b64_e32 v[222:223], v[4:5]
	v_mov_b64_e32 v[224:225], v[12:13]
	v_mov_b64_e32 v[226:227], v[20:21]
	v_mov_b64_e32 v[228:229], v[28:29]
	v_mov_b64_e32 v[230:231], v[36:37]
	global_load_dwordx4 v[0:3], v[4:5], off offset:2048
	s_nop 0
	global_load_dwordx4 v[4:7], v[4:5], off
	s_nop 0
	global_load_dwordx4 v[8:11], v[12:13], off offset:2048
	s_nop 0
	global_load_dwordx4 v[12:15], v[12:13], off
	s_nop 0
	global_load_dwordx4 v[16:19], v[20:21], off offset:2048
	s_nop 0
	global_load_dwordx4 v[20:23], v[20:21], off
	s_nop 0
	global_load_dwordx4 v[24:27], v[28:29], off offset:2048
	s_nop 0
	global_load_dwordx4 v[28:31], v[28:29], off
	s_nop 0
	global_load_dwordx4 v[32:35], v[36:37], off offset:16
	s_nop 0
	global_load_dwordx4 v[36:39], v[36:37], off
	s_mov_b32 s27, s76
